# P5 mid-K hook: all 32 gate loads issued before one wait (32-bit offsets against four scalar bases) instead of two batches with two waits
# baseline (speedup 1.0000x reference)
; #define PG8_STAGE(bufoff, gbase, voff) do { _Pragma("unroll") for (int _i = 0; _i < 2; ++_i) \
;         __builtin_amdgcn_global_load_lds((const unsigned*)((const char*)(gbase) + (voff)[_i]), (LAS unsigned*)(lds + (bufoff) + ldsw + _i * 8192), 16, 0, 0); } while (0)
; #define PG8_LDA(dst, b, h) do { _Pragma("unroll") for (int m = 0; m < 4; ++m) _Pragma("unroll") for (int k = 0; k < 2; ++k) dst[m][k] = *(const LAS bf16x8*)(lds + PG8_SA(b, h) + aoff + m * 2048 + k * 1024); } while (0)
; #define PG8_BAR __builtin_amdgcn_s_barrier()
; template <class Epi>
; DI void gemm_phase(LAS unsigned char* lds, const Gemm g, const StaticOrder& S_, const Epi& E) {
;     ...
;         for (int t = tb; t < te; t += 2) {
;             const bool last = (t == nt - 2);
;             const bool hA = (t >= ksplit), hB = (t + 2 >= ksplit);
;             const char* a1 = (hA ? cA1 : cA0) + (size_t)(t + 1) * kstep;
;             const char* a2 = last ? nA0 : (hB ? cA1 : cA0) + (size_t)(t + 2) * kstep; const char* b2 = last ? nB0 : (hB ? cB1 : cB0) + (size_t)(t + 2) * kstep;
;             const char* a3 = a2 + kstep; const char* b3 = b2 + kstep;
;             PG8_LDB(B0, 0, 0); PG8_SCHED; PG8_LDA(At, 0, 0); PG8_STAGE(PG8_SA(1, 1), a1 + hstepA, voffA);
;             PG8_WAIT_L(8); PG8_BAR; PG8_WAIT_L(0); PG8_MMA(0, 0, At, B0); PG8_BAR; PG8_SCHED;
;             PG8_LDB(B1, 0, 1); PG8_STAGE(PG8_SB(0, 0), b2, voffB);
;             PG8_BAR; PG8_WAIT_L(0); PG8_MMA(0, 1, At, B1); PG8_BAR;
;             PG8_LDA(At, 0, 1); PG8_STAGE(PG8_SA(0, 0), a2, voffA);
;             PG8_BAR; PG8_WAIT_L(0); PG8_MMA(1, 0, At, B0); PG8_BAR; PG8_SCHED;
;             PG8_STAGE(PG8_SB(0, 1), b2 + hstepB, voffB);
;             PG8_WAIT_V(6); PG8_BAR; PG8_MMA(1, 1, At, B1); PG8_BAR;
;             PG8_LDB(B0, 1, 0); PG8_SCHED; PG8_LDA(At, 1, 0); PG8_STAGE(PG8_SA(0, 1), a2 + hstepA, voffA);
;             PG8_WAIT_L(8); PG8_BAR; PG8_WAIT_L(0); PG8_MMA(0, 0, At, B0); PG8_BAR; PG8_SCHED;
;             PG8_LDB(B1, 1, 1); PG8_STAGE(PG8_SB(1, 0), b3, voffB);
;             PG8_BAR; PG8_WAIT_L(0); PG8_MMA(0, 1, At, B1); PG8_BAR;
;             PG8_LDA(At, 1, 1); PG8_STAGE(PG8_SA(1, 0), a3, voffA);
;             PG8_BAR; PG8_WAIT_L(0); PG8_MMA(1, 0, At, B0); PG8_BAR; PG8_SCHED;
;             PG8_STAGE(PG8_SB(1, 1), b3 + hstepB, voffB);
;             PG8_WAIT_V(6); PG8_BAR; PG8_MMA(1, 1, At, B1); PG8_BAR;
.LBB0_450:
	s_add_i32 s82, s14, 2
	s_cmp_gt_u32 s14, 29
	s_cselect_b32 s49, s74, s38
	s_cselect_b32 s48, s75, s39
	s_cselect_b32 s50, s77, s41
	s_cselect_b32 s51, s76, s40
	s_add_u32 s49, s49, s46
	s_addc_u32 s48, s48, s47
	s_add_u32 s49, s49, 0x100
	v_add_u32_e32 v0, s70, v205
	s_addc_u32 s48, s48, 0
	ds_read_b128 v[148:151], v0
	ds_read_b128 v[152:155], v0 offset:1024
	ds_read_b128 v[156:159], v0 offset:2048
	ds_read_b128 v[160:163], v0 offset:3072
	s_add_u32 s51, s51, s46
	s_addc_u32 s50, s50, s47
	s_add_u32 s83, s51, 0x100
	s_addc_u32 s86, s50, 0
	s_cmp_gt_u32 s14, 31
	s_cselect_b32 s84, s74, s38
	s_cselect_b32 s85, s75, s39
	s_cmpk_eq_i32 s46, 0x1f00
	s_cselect_b32 s51, s23, s48
	s_cselect_b32 s50, s78, s49
	s_cselect_b32 s49, s79, s86
	s_cselect_b32 s48, s80, s83
	v_lshl_add_u64 v[2:3], s[84:85], 0, v[140:141]
	v_lshl_add_u64 v[2:3], v[2:3], 0, s[46:47]
	s_add_i32 m0, s37, 0xc000
	ds_read_b128 v[164:167], v208
	ds_read_b128 v[168:171], v208 offset:1024
	ds_read_b128 v[172:175], v208 offset:2048
	ds_read_b128 v[176:179], v208 offset:3072
	ds_read_b128 v[180:183], v208 offset:4096
	ds_read_b128 v[184:187], v208 offset:5120
	ds_read_b128 v[188:191], v208 offset:6144
	ds_read_b128 v[192:195], v208 offset:7168
	global_load_lds_dwordx4 v[2:3], off
	v_lshl_add_u64 v[2:3], s[84:85], 0, v[142:143]
	v_lshl_add_u64 v[2:3], v[2:3], 0, s[46:47]
	s_add_i32 m0, s37, 0xe000
	s_nop 0
	global_load_lds_dwordx4 v[2:3], off
	s_waitcnt lgkmcnt(8)
	s_setprio 1
	s_barrier
	s_waitcnt lgkmcnt(0)
	v_mfma_f32_16x16x32_bf16 v[128:131], v[148:151], v[164:167], v[128:131]
	v_mfma_f32_16x16x32_bf16 v[124:127], v[156:159], v[164:167], v[124:127]
	v_mfma_f32_16x16x32_bf16 v[112:115], v[148:151], v[172:175], v[112:115]
	v_mfma_f32_16x16x32_bf16 v[108:111], v[156:159], v[172:175], v[108:111]
	v_mfma_f32_16x16x32_bf16 v[96:99], v[148:151], v[180:183], v[96:99]
	v_mfma_f32_16x16x32_bf16 v[92:95], v[156:159], v[180:183], v[92:95]
	v_mfma_f32_16x16x32_bf16 v[80:83], v[148:151], v[188:191], v[80:83]
	v_mfma_f32_16x16x32_bf16 v[76:79], v[156:159], v[188:191], v[76:79]
	v_mfma_f32_16x16x32_bf16 v[128:131], v[152:155], v[168:171], v[128:131]
	v_mfma_f32_16x16x32_bf16 v[124:127], v[160:163], v[168:171], v[124:127]
	v_mfma_f32_16x16x32_bf16 v[112:115], v[152:155], v[176:179], v[112:115]
	v_mfma_f32_16x16x32_bf16 v[108:111], v[160:163], v[176:179], v[108:111]
	v_mfma_f32_16x16x32_bf16 v[96:99], v[152:155], v[184:187], v[96:99]
	v_mfma_f32_16x16x32_bf16 v[92:95], v[160:163], v[184:187], v[92:95]
	v_mfma_f32_16x16x32_bf16 v[80:83], v[152:155], v[192:195], v[80:83]
	v_mfma_f32_16x16x32_bf16 v[76:79], v[160:163], v[192:195], v[76:79]
	s_setprio 0
	s_barrier
	s_add_i32 s14, s70, s58
	v_add_u32_e32 v0, s71, v205
	v_lshl_add_u64 v[200:201], s[48:49], 0, v[134:135]
	s_mov_b32 m0, s14
	ds_read_b128 v[196:199], v0
	ds_read_b128 v[210:213], v0 offset:1024
	ds_read_b128 v[214:217], v0 offset:2048
	ds_read_b128 v[218:221], v0 offset:3072
	global_load_lds_dwordx4 v[200:201], off
	v_lshl_add_u64 v[222:223], s[48:49], 0, v[138:139]
	s_add_i32 m0, s14, 0x2000
	s_nop 0
	global_load_lds_dwordx4 v[222:223], off
	s_setprio 1
	s_barrier
	s_waitcnt lgkmcnt(0)
	v_mfma_f32_16x16x32_bf16 v[120:123], v[196:199], v[164:167], v[120:123]
	v_mfma_f32_16x16x32_bf16 v[116:119], v[214:217], v[164:167], v[116:119]
	v_mfma_f32_16x16x32_bf16 v[104:107], v[196:199], v[172:175], v[104:107]
	v_mfma_f32_16x16x32_bf16 v[100:103], v[214:217], v[172:175], v[100:103]
	v_mfma_f32_16x16x32_bf16 v[88:91], v[196:199], v[180:183], v[88:91]
	v_mfma_f32_16x16x32_bf16 v[84:87], v[214:217], v[180:183], v[84:87]
	v_mfma_f32_16x16x32_bf16 v[72:75], v[196:199], v[188:191], v[72:75]
	v_mfma_f32_16x16x32_bf16 v[68:71], v[214:217], v[188:191], v[68:71]
	v_mfma_f32_16x16x32_bf16 v[120:123], v[210:213], v[168:171], v[120:123]
	v_mfma_f32_16x16x32_bf16 v[116:119], v[218:221], v[168:171], v[116:119]
	v_mfma_f32_16x16x32_bf16 v[104:107], v[210:213], v[176:179], v[104:107]
	v_mfma_f32_16x16x32_bf16 v[100:103], v[218:221], v[176:179], v[100:103]
	v_mfma_f32_16x16x32_bf16 v[88:91], v[210:213], v[184:187], v[88:91]
	v_mfma_f32_16x16x32_bf16 v[84:87], v[218:221], v[184:187], v[84:87]
	v_mfma_f32_16x16x32_bf16 v[72:75], v[210:213], v[192:195], v[72:75]
	v_mfma_f32_16x16x32_bf16 v[68:71], v[218:221], v[192:195], v[68:71]
	s_setprio 0
	s_mov_b32 m0, s37
	v_lshl_add_u64 v[224:225], s[50:51], 0, v[132:133]
	s_barrier
	ds_read_b128 v[164:167], v208 offset:16384
	ds_read_b128 v[168:171], v208 offset:17408
	ds_read_b128 v[172:175], v208 offset:18432
	ds_read_b128 v[176:179], v208 offset:19456
	ds_read_b128 v[180:183], v208 offset:20480
	ds_read_b128 v[184:187], v208 offset:21504
	ds_read_b128 v[188:191], v208 offset:22528
	ds_read_b128 v[192:195], v208 offset:23552
	global_load_lds_dwordx4 v[224:225], off
	v_lshl_add_u64 v[226:227], s[50:51], 0, v[136:137]
	s_mov_b32 m0, s59
	s_nop 0
	global_load_lds_dwordx4 v[226:227], off
	s_setprio 1
	s_barrier
	s_waitcnt lgkmcnt(0)
	v_mfma_f32_16x16x32_bf16 v[64:67], v[148:151], v[164:167], v[64:67]
	v_mfma_f32_16x16x32_bf16 v[60:63], v[156:159], v[164:167], v[60:63]
	v_mfma_f32_16x16x32_bf16 v[48:51], v[148:151], v[172:175], v[48:51]
	v_mfma_f32_16x16x32_bf16 v[44:47], v[156:159], v[172:175], v[44:47]
	v_mfma_f32_16x16x32_bf16 v[32:35], v[148:151], v[180:183], v[32:35]
	v_mfma_f32_16x16x32_bf16 v[28:31], v[156:159], v[180:183], v[28:31]
	v_mfma_f32_16x16x32_bf16 v[16:19], v[148:151], v[188:191], v[16:19]
	v_mfma_f32_16x16x32_bf16 v[12:15], v[156:159], v[188:191], v[12:15]
	v_mfma_f32_16x16x32_bf16 v[64:67], v[152:155], v[168:171], v[64:67]
	v_mfma_f32_16x16x32_bf16 v[60:63], v[160:163], v[168:171], v[60:63]
	v_mfma_f32_16x16x32_bf16 v[48:51], v[152:155], v[176:179], v[48:51]
	v_mfma_f32_16x16x32_bf16 v[44:47], v[160:163], v[176:179], v[44:47]
	v_mfma_f32_16x16x32_bf16 v[32:35], v[152:155], v[184:187], v[32:35]
	v_mfma_f32_16x16x32_bf16 v[28:31], v[160:163], v[184:187], v[28:31]
	v_mfma_f32_16x16x32_bf16 v[16:19], v[152:155], v[192:195], v[16:19]
	v_mfma_f32_16x16x32_bf16 v[12:15], v[160:163], v[192:195], v[12:15]
	s_setprio 0
	s_barrier
; #define PG8_STAGE(bufoff, gbase, voff) do { _Pragma("unroll") for (int _i = 0; _i < 2; ++_i) \
;         __builtin_amdgcn_global_load_lds((const unsigned*)((const char*)(gbase) + (voff)[_i]), (LAS unsigned*)(lds + (bufoff) + ldsw + _i * 8192), 16, 0, 0); } while (0)
; #define PG8_LDA(dst, b, h) do { _Pragma("unroll") for (int m = 0; m < 4; ++m) _Pragma("unroll") for (int k = 0; k < 2; ++k) dst[m][k] = *(const LAS bf16x8*)(lds + PG8_SA(b, h) + aoff + m * 2048 + k * 1024); } while (0)
; #define PG8_LDB(dst, b, h) do { _Pragma("unroll") for (int n = 0; n < 2; ++n) _Pragma("unroll") for (int k = 0; k < 2; ++k) dst[n][k] = *(const LAS bf16x8*)(lds + PG8_SB(b, h) + boff + n * 2048 + k * 1024); } while (0)
; #define PG8_MMA(ai, bj, At, Bt) do { __builtin_amdgcn_s_setprio(1); _Pragma("unroll") for (int m = 0; m < 4; ++m) _Pragma("unroll") for (int n = 0; n < 2; ++n) _Pragma("unroll") for (int k = 0; k < 2; ++k) \
;         acc[ai][bj][m][n] = __builtin_amdgcn_mfma_f32_16x16x32_bf16(Bt[n][k], At[m][k], acc[ai][bj][m][n], 0, 0, 0); __builtin_amdgcn_s_setprio(0); } while (0)
; #define PG8_WAIT_V(n) asm volatile("s_waitcnt vmcnt(" #n ")" ::: "memory")
; #define PG8_WAIT_L(n) asm volatile("s_waitcnt lgkmcnt(" #n ")" ::: "memory")
; #define PG8_BAR __builtin_amdgcn_s_barrier()
; #define PG8_SCHED __builtin_amdgcn_sched_barrier(0)
; template <class Epi>
; DI void gemm_phase(LAS unsigned char* lds, const Gemm g, const StaticOrder& S_, const Epi& E) {
;     ...
;             PG8_WAIT_V(6); PG8_BAR; PG8_MMA(1, 1, At, B1); PG8_BAR;
;             PG8_LDB(B0, 1, 0); PG8_SCHED; PG8_LDA(At, 1, 0); PG8_STAGE(PG8_SA(0, 1), a2 + hstepA, voffA);
;             PG8_WAIT_L(8); PG8_BAR; PG8_WAIT_L(0); PG8_MMA(0, 0, At, B0); PG8_BAR; PG8_SCHED;
;             PG8_LDB(B1, 1, 1); PG8_STAGE(PG8_SB(1, 0), b3, voffB);
;             PG8_BAR; PG8_WAIT_L(0); PG8_MMA(0, 1, At, B1); PG8_BAR;
;             PG8_LDA(At, 1, 1); PG8_STAGE(PG8_SA(1, 0), a3, voffA);
;             PG8_BAR; PG8_WAIT_L(0); PG8_MMA(1, 0, At, B0); PG8_BAR; PG8_SCHED;
;             PG8_STAGE(PG8_SB(1, 1), b3 + hstepB, voffB);
;             PG8_WAIT_V(6); PG8_BAR; PG8_MMA(1, 1, At, B1); PG8_BAR;
	s_add_u32 s84, s48, 0x80000
	s_addc_u32 s85, s49, 0
	s_add_i32 s14, s71, s58
	v_lshl_add_u64 v[2:3], s[84:85], 0, v[134:135]
	s_mov_b32 m0, s14
	s_nop 0
	global_load_lds_dwordx4 v[2:3], off
	v_lshl_add_u64 v[2:3], s[84:85], 0, v[138:139]
	s_add_i32 m0, s14, 0x2000
	s_nop 0
	global_load_lds_dwordx4 v[2:3], off
	s_waitcnt vmcnt(6)
	s_setprio 1
	s_barrier
	v_mfma_f32_16x16x32_bf16 v[56:59], v[196:199], v[164:167], v[56:59]
	v_mfma_f32_16x16x32_bf16 v[52:55], v[214:217], v[164:167], v[52:55]
	v_mfma_f32_16x16x32_bf16 v[40:43], v[196:199], v[172:175], v[40:43]
	v_mfma_f32_16x16x32_bf16 v[36:39], v[214:217], v[172:175], v[36:39]
	v_mfma_f32_16x16x32_bf16 v[24:27], v[196:199], v[180:183], v[24:27]
	v_mfma_f32_16x16x32_bf16 v[20:23], v[214:217], v[180:183], v[20:23]
	v_mfma_f32_16x16x32_bf16 v[8:11], v[196:199], v[188:191], v[8:11]
	v_mfma_f32_16x16x32_bf16 v[2:5], v[214:217], v[188:191], v[4:7]
	v_mfma_f32_16x16x32_bf16 v[56:59], v[210:213], v[168:171], v[56:59]
	v_mfma_f32_16x16x32_bf16 v[52:55], v[218:221], v[168:171], v[52:55]
	v_mfma_f32_16x16x32_bf16 v[40:43], v[210:213], v[176:179], v[40:43]
	v_mfma_f32_16x16x32_bf16 v[36:39], v[218:221], v[176:179], v[36:39]
	v_mfma_f32_16x16x32_bf16 v[24:27], v[210:213], v[184:187], v[24:27]
	v_mfma_f32_16x16x32_bf16 v[20:23], v[218:221], v[184:187], v[20:23]
	v_mfma_f32_16x16x32_bf16 v[8:11], v[210:213], v[192:195], v[8:11]
	v_mfma_f32_16x16x32_bf16 v[2:5], v[218:221], v[192:195], v[2:5]
	s_setprio 0
	s_add_i32 s14, 0, 0x18000
	v_add_u32_e32 v0, s14, v205
	s_barrier
	ds_read_b128 v[148:151], v0
	ds_read_b128 v[152:155], v0 offset:1024
	ds_read_b128 v[156:159], v0 offset:2048
	ds_read_b128 v[160:163], v0 offset:3072
	s_add_u32 s50, s50, 0x80000
	s_addc_u32 s51, s51, 0
	s_mov_b32 m0, s60
	v_lshl_add_u64 v[6:7], s[50:51], 0, v[132:133]
	ds_read_b128 v[164:167], v208 offset:32768
	ds_read_b128 v[168:171], v208 offset:33792
	ds_read_b128 v[172:175], v208 offset:34816
	ds_read_b128 v[176:179], v208 offset:35840
	ds_read_b128 v[180:183], v208 offset:36864
	ds_read_b128 v[184:187], v208 offset:37888
	ds_read_b128 v[188:191], v208 offset:38912
	ds_read_b128 v[192:195], v208 offset:39936
	global_load_lds_dwordx4 v[6:7], off
	v_lshl_add_u64 v[6:7], s[50:51], 0, v[136:137]
	s_mov_b32 m0, s61
	s_nop 0
	global_load_lds_dwordx4 v[6:7], off
	s_waitcnt lgkmcnt(8)
	s_setprio 1
	s_barrier
	s_waitcnt lgkmcnt(0)
	v_mfma_f32_16x16x32_bf16 v[128:131], v[148:151], v[164:167], v[128:131]
	v_mfma_f32_16x16x32_bf16 v[124:127], v[156:159], v[164:167], v[124:127]
	v_mfma_f32_16x16x32_bf16 v[112:115], v[148:151], v[172:175], v[112:115]
	v_mfma_f32_16x16x32_bf16 v[108:111], v[156:159], v[172:175], v[108:111]
	v_mfma_f32_16x16x32_bf16 v[96:99], v[148:151], v[180:183], v[96:99]
	v_mfma_f32_16x16x32_bf16 v[92:95], v[156:159], v[180:183], v[92:95]
	v_mfma_f32_16x16x32_bf16 v[80:83], v[148:151], v[188:191], v[80:83]
	v_mfma_f32_16x16x32_bf16 v[76:79], v[156:159], v[188:191], v[76:79]
	v_mfma_f32_16x16x32_bf16 v[128:131], v[152:155], v[168:171], v[128:131]
	v_mfma_f32_16x16x32_bf16 v[124:127], v[160:163], v[168:171], v[124:127]
	v_mfma_f32_16x16x32_bf16 v[112:115], v[152:155], v[176:179], v[112:115]
	v_mfma_f32_16x16x32_bf16 v[108:111], v[160:163], v[176:179], v[108:111]
	v_mfma_f32_16x16x32_bf16 v[96:99], v[152:155], v[184:187], v[96:99]
	v_mfma_f32_16x16x32_bf16 v[92:95], v[160:163], v[184:187], v[92:95]
	v_mfma_f32_16x16x32_bf16 v[80:83], v[152:155], v[192:195], v[80:83]
	v_mfma_f32_16x16x32_bf16 v[76:79], v[160:163], v[192:195], v[76:79]
	s_setprio 0
	s_barrier
	s_add_i32 s50, 0, 0x1c000
	s_add_i32 s14, s14, s58
	v_add_u32_e32 v0, s50, v205
	v_lshl_add_u64 v[6:7], v[200:201], 0, s[16:17]
	s_mov_b32 m0, s14
	ds_read_b128 v[196:199], v0
	ds_read_b128 v[210:213], v0 offset:1024
	ds_read_b128 v[214:217], v0 offset:2048
	ds_read_b128 v[218:221], v0 offset:3072
	global_load_lds_dwordx4 v[6:7], off
	v_lshl_add_u64 v[6:7], v[222:223], 0, s[16:17]
	s_add_i32 m0, s14, 0x2000
	s_nop 0
	global_load_lds_dwordx4 v[6:7], off
	s_setprio 1
	s_barrier
	s_waitcnt lgkmcnt(0)
	v_mfma_f32_16x16x32_bf16 v[120:123], v[196:199], v[164:167], v[120:123]
	v_mfma_f32_16x16x32_bf16 v[116:119], v[214:217], v[164:167], v[116:119]
	v_mfma_f32_16x16x32_bf16 v[104:107], v[196:199], v[172:175], v[104:107]
	v_mfma_f32_16x16x32_bf16 v[100:103], v[214:217], v[172:175], v[100:103]
	v_mfma_f32_16x16x32_bf16 v[88:91], v[196:199], v[180:183], v[88:91]
	v_mfma_f32_16x16x32_bf16 v[84:87], v[214:217], v[180:183], v[84:87]
	v_mfma_f32_16x16x32_bf16 v[72:75], v[196:199], v[188:191], v[72:75]
	v_mfma_f32_16x16x32_bf16 v[68:71], v[214:217], v[188:191], v[68:71]
	v_mfma_f32_16x16x32_bf16 v[120:123], v[210:213], v[168:171], v[120:123]
	v_mfma_f32_16x16x32_bf16 v[116:119], v[218:221], v[168:171], v[116:119]
	v_mfma_f32_16x16x32_bf16 v[104:107], v[210:213], v[176:179], v[104:107]
	v_mfma_f32_16x16x32_bf16 v[100:103], v[218:221], v[176:179], v[100:103]
	v_mfma_f32_16x16x32_bf16 v[88:91], v[210:213], v[184:187], v[88:91]
	v_mfma_f32_16x16x32_bf16 v[84:87], v[218:221], v[184:187], v[84:87]
	v_mfma_f32_16x16x32_bf16 v[72:75], v[210:213], v[192:195], v[72:75]
	v_mfma_f32_16x16x32_bf16 v[68:71], v[218:221], v[192:195], v[68:71]
	s_setprio 0
	s_mov_b32 m0, s66
	v_lshl_add_u64 v[6:7], v[224:225], 0, s[16:17]
	s_barrier
	ds_read_b128 v[164:167], v208 offset:49152
	ds_read_b128 v[168:171], v208 offset:50176
	ds_read_b128 v[172:175], v208 offset:51200
	ds_read_b128 v[176:179], v208 offset:52224
	ds_read_b128 v[180:183], v208 offset:53248
	ds_read_b128 v[184:187], v208 offset:54272
	ds_read_b128 v[188:191], v208 offset:55296
	ds_read_b128 v[192:195], v208 offset:56320
	global_load_lds_dwordx4 v[6:7], off
	v_lshl_add_u64 v[6:7], v[226:227], 0, s[16:17]
	s_mov_b32 m0, s67
	s_nop 0
	global_load_lds_dwordx4 v[6:7], off
	s_setprio 1
	s_barrier
; #define PG8_STAGE(bufoff, gbase, voff) do { _Pragma("unroll") for (int _i = 0; _i < 2; ++_i) \
;         __builtin_amdgcn_global_load_lds((const unsigned*)((const char*)(gbase) + (voff)[_i]), (LAS unsigned*)(lds + (bufoff) + ldsw + _i * 8192), 16, 0, 0); } while (0)
; #define PG8_LDA(dst, b, h) do { _Pragma("unroll") for (int m = 0; m < 4; ++m) _Pragma("unroll") for (int k = 0; k < 2; ++k) dst[m][k] = *(const LAS bf16x8*)(lds + PG8_SA(b, h) + aoff + m * 2048 + k * 1024); } while (0)
; #define PG8_MMA(ai, bj, At, Bt) do { __builtin_amdgcn_s_setprio(1); _Pragma("unroll") for (int m = 0; m < 4; ++m) _Pragma("unroll") for (int n = 0; n < 2; ++n) _Pragma("unroll") for (int k = 0; k < 2; ++k) \
;         acc[ai][bj][m][n] = __builtin_amdgcn_mfma_f32_16x16x32_bf16(Bt[n][k], At[m][k], acc[ai][bj][m][n], 0, 0, 0); __builtin_amdgcn_s_setprio(0); } while (0)
; #define PG8_WAIT_V(n) asm volatile("s_waitcnt vmcnt(" #n ")" ::: "memory")
; #define PG8_WAIT_L(n) asm volatile("s_waitcnt lgkmcnt(" #n ")" ::: "memory")
; template <class Epi>
; DI void gemm_phase(LAS unsigned char* lds, const Gemm g, const StaticOrder& S_, const Epi& E) {
;     ...
;             PG8_BAR; PG8_WAIT_L(0); PG8_MMA(0, 1, At, B1); PG8_BAR;
;             PG8_LDA(At, 1, 1); PG8_STAGE(PG8_SA(1, 0), a3, voffA);
;             PG8_BAR; PG8_WAIT_L(0); PG8_MMA(1, 0, At, B0); PG8_BAR; PG8_SCHED;
;             PG8_STAGE(PG8_SB(1, 1), b3 + hstepB, voffB);
;             PG8_WAIT_V(6); PG8_BAR; PG8_MMA(1, 1, At, B1); PG8_BAR;
;         }
;         if constexpr (Epi::MID) { if (hf == 0) E.mid(acc, cur, wr, wc, fr, fq); }
;     DI void mid(f32x4 (&acc)[2][2][4][2], const pg8::Unit& u, int wr, int wc, int fr, int fq) const {
;         const unsigned char* zm = ws + WS_ZM;
;         unsigned b0_ = (unsigned)u.pn * (unsigned)(S * 256) + (unsigned)(u.pm * 256 + wr * 64 + fr) * 256u + (unsigned)(wc * 32 + 8 * fq);
;         asm volatile("" : "+v"(b0_));
;         u32x2 g1[2][4][2], g2[2][4][2];
; #pragma unroll
;         for (int ai = 0; ai < 2; ++ai)
; #pragma unroll
;             for (int m = 0; m < 4; ++m)
; #pragma unroll
;                 for (int bj = 0; bj < 2; ++bj) { const unsigned bo = b0_ + (unsigned)(ai * 128 + m * 16) * 256u + bj * 128u;
;                     g1[ai][m][bj] = *(const u32x2*)(zm + bo); g2[ai][m][bj] = *(const u32x2*)(zm + bo + (unsigned)(8 * S * 256)); }
	s_waitcnt lgkmcnt(0)
	v_mfma_f32_16x16x32_bf16 v[64:67], v[148:151], v[164:167], v[64:67]
	v_mfma_f32_16x16x32_bf16 v[60:63], v[156:159], v[164:167], v[60:63]
	v_mfma_f32_16x16x32_bf16 v[48:51], v[148:151], v[172:175], v[48:51]
	v_mfma_f32_16x16x32_bf16 v[44:47], v[156:159], v[172:175], v[44:47]
	v_mfma_f32_16x16x32_bf16 v[32:35], v[148:151], v[180:183], v[32:35]
	v_mfma_f32_16x16x32_bf16 v[28:31], v[156:159], v[180:183], v[28:31]
	v_mfma_f32_16x16x32_bf16 v[16:19], v[148:151], v[188:191], v[16:19]
	v_mfma_f32_16x16x32_bf16 v[12:15], v[156:159], v[188:191], v[12:15]
	v_mfma_f32_16x16x32_bf16 v[64:67], v[152:155], v[168:171], v[64:67]
	v_mfma_f32_16x16x32_bf16 v[60:63], v[160:163], v[168:171], v[60:63]
	v_mfma_f32_16x16x32_bf16 v[48:51], v[152:155], v[176:179], v[48:51]
	v_mfma_f32_16x16x32_bf16 v[44:47], v[160:163], v[176:179], v[44:47]
	v_mfma_f32_16x16x32_bf16 v[32:35], v[152:155], v[184:187], v[32:35]
	v_mfma_f32_16x16x32_bf16 v[28:31], v[160:163], v[184:187], v[28:31]
	v_mfma_f32_16x16x32_bf16 v[16:19], v[152:155], v[192:195], v[16:19]
	v_mfma_f32_16x16x32_bf16 v[12:15], v[160:163], v[192:195], v[12:15]
	s_setprio 0
	s_barrier
	s_add_u32 s48, s48, 0x80080
	s_addc_u32 s49, s49, 0
	s_add_i32 s14, s50, s58
	v_lshl_add_u64 v[6:7], s[48:49], 0, v[134:135]
	s_mov_b32 m0, s14
	s_nop 0
	global_load_lds_dwordx4 v[6:7], off
	v_lshl_add_u64 v[6:7], s[48:49], 0, v[138:139]
	s_add_i32 m0, s14, 0x2000
	s_nop 0
	global_load_lds_dwordx4 v[6:7], off
	s_waitcnt vmcnt(6)
	s_setprio 1
	s_barrier
	v_mfma_f32_16x16x32_bf16 v[56:59], v[196:199], v[164:167], v[56:59]
	v_mfma_f32_16x16x32_bf16 v[52:55], v[214:217], v[164:167], v[52:55]
	v_mfma_f32_16x16x32_bf16 v[40:43], v[196:199], v[172:175], v[40:43]
	v_mfma_f32_16x16x32_bf16 v[36:39], v[214:217], v[172:175], v[36:39]
	v_mfma_f32_16x16x32_bf16 v[24:27], v[196:199], v[180:183], v[24:27]
	v_mfma_f32_16x16x32_bf16 v[20:23], v[214:217], v[180:183], v[20:23]
	v_mfma_f32_16x16x32_bf16 v[6:9], v[196:199], v[188:191], v[8:11]
	v_mfma_f32_16x16x32_bf16 v[2:5], v[214:217], v[188:191], v[2:5]
	v_mfma_f32_16x16x32_bf16 v[56:59], v[210:213], v[168:171], v[56:59]
	v_mfma_f32_16x16x32_bf16 v[52:55], v[218:221], v[168:171], v[52:55]
	v_mfma_f32_16x16x32_bf16 v[40:43], v[210:213], v[176:179], v[40:43]
	v_mfma_f32_16x16x32_bf16 v[36:39], v[218:221], v[176:179], v[36:39]
	v_mfma_f32_16x16x32_bf16 v[24:27], v[210:213], v[184:187], v[24:27]
	v_mfma_f32_16x16x32_bf16 v[20:23], v[218:221], v[184:187], v[20:23]
	v_mfma_f32_16x16x32_bf16 v[8:11], v[210:213], v[192:195], v[6:9]
	v_mfma_f32_16x16x32_bf16 v[4:7], v[218:221], v[192:195], v[2:5]
	s_setprio 0
	s_add_u32 s46, s46, 0x100
	s_addc_u32 s47, s47, 0
	s_cmp_ge_u32 s82, s81
	s_mov_b32 s14, s82
	s_barrier
	s_cbranch_scc0 .LBB0_450
	s_and_b64 vcc, exec, s[44:45]
	s_cbranch_vccz .LBB0_448
	v_mov_b32_e32 v0, v209
	v_add_u32_e32 v227, 0x1000, v0
	v_add_u32_e32 v228, 0x2000, v0
	v_add_u32_e32 v229, 0x3000, v0
	s_add_u32 s82, s18, 0x8000
	s_addc_u32 s83, s19, 0
	s_add_u32 s84, s18, 0x2000000
	s_addc_u32 s85, s19, 0
	s_add_u32 s86, s18, 0x2008000
	s_addc_u32 s87, s19, 0
	global_load_dwordx2 v[200:201], v0, s[84:85] offset:128
	global_load_dwordx2 v[210:211], v0, s[18:19] offset:128
	global_load_dwordx2 v[196:197], v227, s[18:19]
	global_load_dwordx2 v[192:193], v227, s[18:19] offset:128
	global_load_dwordx2 v[188:189], v228, s[18:19]
	global_load_dwordx2 v[212:213], v0, s[18:19]
	global_load_dwordx2 v[214:215], v0, s[84:85]
	global_load_dwordx2 v[198:199], v227, s[84:85]
	global_load_dwordx2 v[190:191], v228, s[84:85]
	global_load_dwordx2 v[186:187], v228, s[18:19] offset:128
	global_load_dwordx2 v[182:183], v229, s[18:19]
	global_load_dwordx2 v[178:179], v229, s[18:19] offset:128
	global_load_dwordx2 v[174:175], v0, s[82:83]
	global_load_dwordx2 v[184:185], v229, s[84:85]
	global_load_dwordx2 v[180:181], v229, s[84:85] offset:128
	global_load_dwordx2 v[176:177], v0, s[86:87]
	global_load_dwordx2 v[170:171], v0, s[86:87] offset:128
	global_load_dwordx2 v[172:173], v0, s[82:83] offset:128
	global_load_dwordx2 v[166:167], v227, s[82:83]
	global_load_dwordx2 v[162:163], v227, s[82:83] offset:128
	global_load_dwordx2 v[158:159], v228, s[82:83]
	global_load_dwordx2 v[168:169], v227, s[86:87]
	global_load_dwordx2 v[164:165], v227, s[86:87] offset:128
	global_load_dwordx2 v[160:161], v228, s[86:87]
	global_load_dwordx2 v[154:155], v228, s[86:87] offset:128
	global_load_dwordx2 v[220:221], v227, s[84:85] offset:128
	global_load_dwordx2 v[194:195], v228, s[84:85] offset:128
	global_load_dwordx2 v[2:3], v229, s[82:83] offset:128
	global_load_dwordx2 v[156:157], v228, s[82:83] offset:128
	global_load_dwordx2 v[150:151], v229, s[82:83]
	global_load_dwordx2 v[152:153], v229, s[86:87]
	global_load_dwordx2 v[148:149], v229, s[86:87] offset:128
	s_waitcnt vmcnt(0)
; DI float rcpf_(float x) { return __builtin_amdgcn_rcpf(x); }
; DI float ub(unsigned w, int i) { return (float)((w >> (8 * i)) & 0xffu); }
;     DI void mid(f32x4 (&acc)[2][2][4][2], const pg8::Unit& u, int wr, int wc, int fr, int fq) const {
;     ...
;                 for (int bj = 0; bj < 2; ++bj) { const unsigned bo = b0_ + (unsigned)(ai * 128 + m * 16) * 256u + bj * 128u;
;                     g1[ai][m][bj] = *(const u32x2*)(zm + bo); g2[ai][m][bj] = *(const u32x2*)(zm + bo + (unsigned)(8 * S * 256)); }
; #pragma unroll
;         for (int ai = 0; ai < 2; ++ai)
; #pragma unroll
;             for (int m = 0; m < 4; ++m)
; #pragma unroll
;                 for (int bj = 0; bj < 2; ++bj)
; #pragma unroll
;                     for (int e = 0; e < 8; ++e)
;                         acc[ai][bj][m][e >> 2][e & 3] *= ub(g1[ai][m][bj][e >> 2], e & 3) * rcpf_(ub(g2[ai][m][bj][e >> 2], e & 3));
	v_cvt_f32_ubyte1_e32 v225, v212
	v_cvt_f32_ubyte0_e32 v224, v212
	v_cvt_f32_ubyte0_e32 v0, v214
	v_rcp_iflag_f32_e32 v216, v0
	v_cvt_f32_ubyte1_e32 v0, v214
	v_rcp_iflag_f32_e32 v217, v0
	v_cvt_f32_ubyte2_e32 v0, v214
	v_rcp_iflag_f32_e32 v218, v0
	v_cvt_f32_ubyte3_e32 v0, v214
	v_rcp_iflag_f32_e32 v219, v0
	v_pk_mul_f32 v[216:217], v[216:217], v[224:225]
	v_cvt_f32_ubyte0_e32 v0, v215
	v_pk_mul_f32 v[128:129], v[128:129], v[216:217]
	v_rcp_iflag_f32_e32 v216, v0
	v_cvt_f32_ubyte1_e32 v0, v215
	v_rcp_iflag_f32_e32 v217, v0
	v_cvt_f32_ubyte3_e32 v223, v212
	v_cvt_f32_ubyte2_e32 v222, v212
	v_cvt_f32_ubyte2_e32 v0, v215
	v_pk_mul_f32 v[218:219], v[218:219], v[222:223]
	v_rcp_iflag_f32_e32 v214, v0
	v_cvt_f32_ubyte3_e32 v0, v215
	v_cvt_f32_ubyte1_e32 v223, v213
	v_cvt_f32_ubyte0_e32 v222, v213
	v_pk_mul_f32 v[130:131], v[130:131], v[218:219]
	v_rcp_iflag_f32_e32 v215, v0
	v_cvt_f32_ubyte3_e32 v219, v213
	v_cvt_f32_ubyte2_e32 v218, v213
	v_pk_mul_f32 v[212:213], v[216:217], v[222:223]
	v_cvt_f32_ubyte0_e32 v0, v200
	v_pk_mul_f32 v[124:125], v[124:125], v[212:213]
	v_rcp_iflag_f32_e32 v212, v0
	v_cvt_f32_ubyte1_e32 v0, v200
	v_rcp_iflag_f32_e32 v213, v0
	v_pk_mul_f32 v[214:215], v[214:215], v[218:219]
	v_cvt_f32_ubyte2_e32 v0, v200
	v_pk_mul_f32 v[126:127], v[126:127], v[214:215]
	v_rcp_iflag_f32_e32 v214, v0
	v_cvt_f32_ubyte3_e32 v0, v200
	v_cvt_f32_ubyte1_e32 v219, v210
	v_cvt_f32_ubyte0_e32 v218, v210
	v_rcp_iflag_f32_e32 v215, v0
	v_pk_mul_f32 v[212:213], v[212:213], v[218:219]
	v_cvt_f32_ubyte0_e32 v0, v201
	v_pk_mul_f32 v[120:121], v[120:121], v[212:213]
	v_rcp_iflag_f32_e32 v212, v0
	v_cvt_f32_ubyte1_e32 v0, v201
	v_rcp_iflag_f32_e32 v213, v0
	v_cvt_f32_ubyte2_e32 v0, v201
	v_rcp_iflag_f32_e32 v200, v0
	v_cvt_f32_ubyte3_e32 v0, v201
	v_rcp_iflag_f32_e32 v201, v0
	v_cvt_f32_ubyte3_e32 v217, v210
	v_cvt_f32_ubyte2_e32 v216, v210
	v_pk_mul_f32 v[214:215], v[214:215], v[216:217]
	v_cvt_f32_ubyte0_e32 v0, v198
	v_pk_mul_f32 v[122:123], v[122:123], v[214:215]
	v_cvt_f32_ubyte3_e32 v215, v211
	v_cvt_f32_ubyte2_e32 v214, v211
	v_pk_mul_f32 v[200:201], v[200:201], v[214:215]
	v_cvt_f32_ubyte1_e32 v217, v211
	v_pk_mul_f32 v[118:119], v[118:119], v[200:201]
	v_rcp_iflag_f32_e32 v200, v0
	v_cvt_f32_ubyte1_e32 v0, v198
	v_rcp_iflag_f32_e32 v201, v0
	v_cvt_f32_ubyte0_e32 v216, v211
	v_pk_mul_f32 v[210:211], v[212:213], v[216:217]
	v_cvt_f32_ubyte2_e32 v0, v198
	v_pk_mul_f32 v[116:117], v[116:117], v[210:211]
	v_rcp_iflag_f32_e32 v210, v0
	v_cvt_f32_ubyte3_e32 v0, v198
	v_cvt_f32_ubyte1_e32 v215, v196
	v_cvt_f32_ubyte0_e32 v214, v196
	v_rcp_iflag_f32_e32 v211, v0
	v_pk_mul_f32 v[200:201], v[200:201], v[214:215]
	v_cvt_f32_ubyte0_e32 v0, v199
	v_pk_mul_f32 v[112:113], v[112:113], v[200:201]
	v_rcp_iflag_f32_e32 v200, v0
	v_cvt_f32_ubyte1_e32 v0, v199
	v_rcp_iflag_f32_e32 v201, v0
	v_cvt_f32_ubyte3_e32 v213, v196
	v_cvt_f32_ubyte2_e32 v212, v196
	v_cvt_f32_ubyte2_e32 v0, v199
	v_pk_mul_f32 v[210:211], v[210:211], v[212:213]
	v_rcp_iflag_f32_e32 v198, v0
	v_cvt_f32_ubyte3_e32 v0, v199
	v_cvt_f32_ubyte1_e32 v213, v197
	v_cvt_f32_ubyte0_e32 v212, v197
	v_pk_mul_f32 v[114:115], v[114:115], v[210:211]
	v_rcp_iflag_f32_e32 v199, v0
	v_cvt_f32_ubyte3_e32 v211, v197
	v_cvt_f32_ubyte2_e32 v210, v197
	v_pk_mul_f32 v[196:197], v[200:201], v[212:213]
	v_cvt_f32_ubyte0_e32 v0, v220
	v_pk_mul_f32 v[108:109], v[108:109], v[196:197]
	v_rcp_iflag_f32_e32 v196, v0
	v_cvt_f32_ubyte1_e32 v0, v220
	v_rcp_iflag_f32_e32 v197, v0
	v_pk_mul_f32 v[198:199], v[198:199], v[210:211]
	v_cvt_f32_ubyte2_e32 v0, v220
	v_pk_mul_f32 v[110:111], v[110:111], v[198:199]
	v_rcp_iflag_f32_e32 v198, v0
	v_cvt_f32_ubyte3_e32 v0, v220
	v_cvt_f32_ubyte1_e32 v211, v192
	v_cvt_f32_ubyte0_e32 v210, v192
	v_rcp_iflag_f32_e32 v199, v0
	v_pk_mul_f32 v[196:197], v[196:197], v[210:211]
	v_cvt_f32_ubyte0_e32 v0, v221
	v_pk_mul_f32 v[104:105], v[104:105], v[196:197]
	v_rcp_iflag_f32_e32 v196, v0
	v_cvt_f32_ubyte1_e32 v0, v221
	v_rcp_iflag_f32_e32 v197, v0
	v_cvt_f32_ubyte3_e32 v201, v192
	v_cvt_f32_ubyte2_e32 v200, v192
	v_pk_mul_f32 v[198:199], v[198:199], v[200:201]
	v_cvt_f32_ubyte2_e32 v0, v221
	v_pk_mul_f32 v[106:107], v[106:107], v[198:199]
	v_rcp_iflag_f32_e32 v198, v0
	v_cvt_f32_ubyte3_e32 v0, v221
	v_cvt_f32_ubyte1_e32 v211, v193
	v_cvt_f32_ubyte0_e32 v210, v193
	v_rcp_iflag_f32_e32 v199, v0
	v_cvt_f32_ubyte3_e32 v201, v193
	v_cvt_f32_ubyte2_e32 v200, v193
	v_pk_mul_f32 v[192:193], v[196:197], v[210:211]
	v_cvt_f32_ubyte0_e32 v0, v190
	v_pk_mul_f32 v[100:101], v[100:101], v[192:193]
	v_rcp_iflag_f32_e32 v192, v0
	v_cvt_f32_ubyte1_e32 v0, v190
	v_rcp_iflag_f32_e32 v193, v0
	v_pk_mul_f32 v[196:197], v[198:199], v[200:201]
	v_cvt_f32_ubyte2_e32 v0, v190
	v_pk_mul_f32 v[102:103], v[102:103], v[196:197]
	v_rcp_iflag_f32_e32 v196, v0
	v_cvt_f32_ubyte3_e32 v0, v190
	v_cvt_f32_ubyte1_e32 v201, v188
	v_cvt_f32_ubyte0_e32 v200, v188
	v_rcp_iflag_f32_e32 v197, v0
	v_pk_mul_f32 v[192:193], v[192:193], v[200:201]
	v_cvt_f32_ubyte0_e32 v0, v191
	v_pk_mul_f32 v[96:97], v[96:97], v[192:193]
	v_rcp_iflag_f32_e32 v192, v0
	v_cvt_f32_ubyte1_e32 v0, v191
	v_rcp_iflag_f32_e32 v193, v0
	v_cvt_f32_ubyte3_e32 v199, v188
	v_cvt_f32_ubyte2_e32 v198, v188
	v_cvt_f32_ubyte2_e32 v0, v191
	v_pk_mul_f32 v[196:197], v[196:197], v[198:199]
	v_rcp_iflag_f32_e32 v190, v0
	v_cvt_f32_ubyte3_e32 v0, v191
	v_cvt_f32_ubyte1_e32 v199, v189
	v_cvt_f32_ubyte0_e32 v198, v189
	v_pk_mul_f32 v[98:99], v[98:99], v[196:197]
	v_rcp_iflag_f32_e32 v191, v0
	v_cvt_f32_ubyte3_e32 v197, v189
	v_cvt_f32_ubyte2_e32 v196, v189
	v_pk_mul_f32 v[188:189], v[192:193], v[198:199]
	v_cvt_f32_ubyte0_e32 v0, v194
	v_pk_mul_f32 v[92:93], v[92:93], v[188:189]
; DI float rcpf_(float x) { return __builtin_amdgcn_rcpf(x); }
; DI float ub(unsigned w, int i) { return (float)((w >> (8 * i)) & 0xffu); }
;     DI void mid(f32x4 (&acc)[2][2][4][2], const pg8::Unit& u, int wr, int wc, int fr, int fq) const {
;     ...
; #pragma unroll
;         for (int ai = 0; ai < 2; ++ai)
; #pragma unroll
;             for (int m = 0; m < 4; ++m)
; #pragma unroll
;                 for (int bj = 0; bj < 2; ++bj)
; #pragma unroll
;                     for (int e = 0; e < 8; ++e)
;                         acc[ai][bj][m][e >> 2][e & 3] *= ub(g1[ai][m][bj][e >> 2], e & 3) * rcpf_(ub(g2[ai][m][bj][e >> 2], e & 3));
	v_rcp_iflag_f32_e32 v188, v0
	v_cvt_f32_ubyte1_e32 v0, v194
	v_rcp_iflag_f32_e32 v189, v0
	v_pk_mul_f32 v[190:191], v[190:191], v[196:197]
	v_cvt_f32_ubyte2_e32 v0, v194
	v_pk_mul_f32 v[94:95], v[94:95], v[190:191]
	v_rcp_iflag_f32_e32 v190, v0
	v_cvt_f32_ubyte3_e32 v0, v194
	v_cvt_f32_ubyte1_e32 v197, v186
	v_cvt_f32_ubyte0_e32 v196, v186
	v_rcp_iflag_f32_e32 v191, v0
	v_pk_mul_f32 v[188:189], v[188:189], v[196:197]
	v_cvt_f32_ubyte0_e32 v0, v195
	v_pk_mul_f32 v[88:89], v[88:89], v[188:189]
	v_rcp_iflag_f32_e32 v188, v0
	v_cvt_f32_ubyte1_e32 v0, v195
	v_rcp_iflag_f32_e32 v189, v0
	v_cvt_f32_ubyte3_e32 v193, v186
	v_cvt_f32_ubyte2_e32 v192, v186
	v_pk_mul_f32 v[190:191], v[190:191], v[192:193]
	v_cvt_f32_ubyte2_e32 v0, v195
	v_pk_mul_f32 v[90:91], v[90:91], v[190:191]
	v_rcp_iflag_f32_e32 v190, v0
	v_cvt_f32_ubyte3_e32 v0, v195
	v_cvt_f32_ubyte1_e32 v195, v187
	v_cvt_f32_ubyte0_e32 v194, v187
	v_rcp_iflag_f32_e32 v191, v0
	v_cvt_f32_ubyte3_e32 v193, v187
	v_cvt_f32_ubyte2_e32 v192, v187
	v_pk_mul_f32 v[186:187], v[188:189], v[194:195]
	v_cvt_f32_ubyte0_e32 v0, v184
	v_pk_mul_f32 v[84:85], v[84:85], v[186:187]
	v_rcp_iflag_f32_e32 v186, v0
	v_cvt_f32_ubyte1_e32 v0, v184
	v_rcp_iflag_f32_e32 v187, v0
	v_pk_mul_f32 v[188:189], v[190:191], v[192:193]
	v_cvt_f32_ubyte2_e32 v0, v184
	v_pk_mul_f32 v[86:87], v[86:87], v[188:189]
	v_rcp_iflag_f32_e32 v188, v0
	v_cvt_f32_ubyte3_e32 v0, v184
	v_cvt_f32_ubyte1_e32 v193, v182
	v_cvt_f32_ubyte0_e32 v192, v182
	v_rcp_iflag_f32_e32 v189, v0
	v_pk_mul_f32 v[186:187], v[186:187], v[192:193]
	v_cvt_f32_ubyte0_e32 v0, v185
	v_pk_mul_f32 v[80:81], v[80:81], v[186:187]
	v_rcp_iflag_f32_e32 v186, v0
	v_cvt_f32_ubyte1_e32 v0, v185
	v_rcp_iflag_f32_e32 v187, v0
	v_cvt_f32_ubyte3_e32 v191, v182
	v_cvt_f32_ubyte2_e32 v190, v182
	v_cvt_f32_ubyte2_e32 v0, v185
	v_pk_mul_f32 v[188:189], v[188:189], v[190:191]
	v_rcp_iflag_f32_e32 v184, v0
	v_cvt_f32_ubyte3_e32 v0, v185
	v_cvt_f32_ubyte1_e32 v191, v183
	v_cvt_f32_ubyte0_e32 v190, v183
	v_pk_mul_f32 v[82:83], v[82:83], v[188:189]
	v_rcp_iflag_f32_e32 v185, v0
	v_cvt_f32_ubyte3_e32 v189, v183
	v_cvt_f32_ubyte2_e32 v188, v183
	v_pk_mul_f32 v[182:183], v[186:187], v[190:191]
	v_cvt_f32_ubyte0_e32 v0, v180
	v_pk_mul_f32 v[76:77], v[76:77], v[182:183]
	v_rcp_iflag_f32_e32 v182, v0
	v_cvt_f32_ubyte1_e32 v0, v180
	v_rcp_iflag_f32_e32 v183, v0
	v_pk_mul_f32 v[184:185], v[184:185], v[188:189]
	v_cvt_f32_ubyte2_e32 v0, v180
	v_pk_mul_f32 v[78:79], v[78:79], v[184:185]
	v_rcp_iflag_f32_e32 v184, v0
	v_cvt_f32_ubyte3_e32 v0, v180
	v_cvt_f32_ubyte1_e32 v189, v178
	v_cvt_f32_ubyte0_e32 v188, v178
	v_rcp_iflag_f32_e32 v185, v0
	v_pk_mul_f32 v[182:183], v[182:183], v[188:189]
	v_cvt_f32_ubyte0_e32 v0, v181
	v_pk_mul_f32 v[72:73], v[72:73], v[182:183]
	v_rcp_iflag_f32_e32 v182, v0
	v_cvt_f32_ubyte1_e32 v0, v181
	v_rcp_iflag_f32_e32 v183, v0
	v_cvt_f32_ubyte3_e32 v187, v178
	v_cvt_f32_ubyte2_e32 v186, v178
	v_cvt_f32_ubyte2_e32 v0, v181
	v_pk_mul_f32 v[184:185], v[184:185], v[186:187]
	v_rcp_iflag_f32_e32 v180, v0
	v_cvt_f32_ubyte3_e32 v0, v181
	v_cvt_f32_ubyte1_e32 v187, v179
	v_cvt_f32_ubyte0_e32 v186, v179
	v_pk_mul_f32 v[74:75], v[74:75], v[184:185]
	v_rcp_iflag_f32_e32 v181, v0
	v_cvt_f32_ubyte3_e32 v185, v179
	v_cvt_f32_ubyte2_e32 v184, v179
	v_pk_mul_f32 v[178:179], v[182:183], v[186:187]
	v_cvt_f32_ubyte0_e32 v0, v176
	v_pk_mul_f32 v[68:69], v[68:69], v[178:179]
	v_rcp_iflag_f32_e32 v178, v0
	v_cvt_f32_ubyte1_e32 v0, v176
	v_rcp_iflag_f32_e32 v179, v0
	v_pk_mul_f32 v[180:181], v[180:181], v[184:185]
	v_cvt_f32_ubyte2_e32 v0, v176
	v_pk_mul_f32 v[70:71], v[70:71], v[180:181]
	v_rcp_iflag_f32_e32 v180, v0
	v_cvt_f32_ubyte3_e32 v0, v176
	v_cvt_f32_ubyte1_e32 v185, v174
	v_cvt_f32_ubyte0_e32 v184, v174
	v_rcp_iflag_f32_e32 v181, v0
	v_pk_mul_f32 v[178:179], v[178:179], v[184:185]
	v_cvt_f32_ubyte0_e32 v0, v177
	v_pk_mul_f32 v[64:65], v[64:65], v[178:179]
	v_rcp_iflag_f32_e32 v178, v0
	v_cvt_f32_ubyte1_e32 v0, v177
	v_rcp_iflag_f32_e32 v179, v0
	v_cvt_f32_ubyte3_e32 v183, v174
	v_cvt_f32_ubyte2_e32 v182, v174
	v_cvt_f32_ubyte2_e32 v0, v177
	v_pk_mul_f32 v[180:181], v[180:181], v[182:183]
	v_rcp_iflag_f32_e32 v176, v0
	v_cvt_f32_ubyte3_e32 v0, v177
	v_cvt_f32_ubyte1_e32 v183, v175
	v_cvt_f32_ubyte0_e32 v182, v175
	v_pk_mul_f32 v[66:67], v[66:67], v[180:181]
	v_rcp_iflag_f32_e32 v177, v0
	v_cvt_f32_ubyte3_e32 v181, v175
	v_cvt_f32_ubyte2_e32 v180, v175
	v_pk_mul_f32 v[174:175], v[178:179], v[182:183]
	v_cvt_f32_ubyte0_e32 v0, v170
	v_pk_mul_f32 v[60:61], v[60:61], v[174:175]
	v_rcp_iflag_f32_e32 v174, v0
	v_cvt_f32_ubyte1_e32 v0, v170
	v_rcp_iflag_f32_e32 v175, v0
	v_pk_mul_f32 v[176:177], v[176:177], v[180:181]
	v_cvt_f32_ubyte2_e32 v0, v170
	v_pk_mul_f32 v[62:63], v[62:63], v[176:177]
	v_rcp_iflag_f32_e32 v176, v0
	v_cvt_f32_ubyte3_e32 v0, v170
	v_cvt_f32_ubyte1_e32 v181, v172
	v_cvt_f32_ubyte0_e32 v180, v172
	v_rcp_iflag_f32_e32 v177, v0
	v_pk_mul_f32 v[174:175], v[174:175], v[180:181]
	v_cvt_f32_ubyte0_e32 v0, v171
	v_pk_mul_f32 v[56:57], v[56:57], v[174:175]
	v_rcp_iflag_f32_e32 v174, v0
	v_cvt_f32_ubyte1_e32 v0, v171
	v_rcp_iflag_f32_e32 v175, v0
	v_cvt_f32_ubyte2_e32 v0, v171
	v_rcp_iflag_f32_e32 v170, v0
	v_cvt_f32_ubyte3_e32 v0, v171
	v_rcp_iflag_f32_e32 v171, v0
	v_cvt_f32_ubyte3_e32 v179, v172
	v_cvt_f32_ubyte2_e32 v178, v172
	v_pk_mul_f32 v[176:177], v[176:177], v[178:179]
	v_cvt_f32_ubyte0_e32 v0, v168
	v_pk_mul_f32 v[58:59], v[58:59], v[176:177]
	v_cvt_f32_ubyte3_e32 v177, v173
	v_cvt_f32_ubyte2_e32 v176, v173
	v_pk_mul_f32 v[170:171], v[170:171], v[176:177]
	v_cvt_f32_ubyte1_e32 v179, v173
	v_pk_mul_f32 v[54:55], v[54:55], v[170:171]
	v_rcp_iflag_f32_e32 v170, v0
; DI float rcpf_(float x) { return __builtin_amdgcn_rcpf(x); }
; DI float ub(unsigned w, int i) { return (float)((w >> (8 * i)) & 0xffu); }
;     DI void mid(f32x4 (&acc)[2][2][4][2], const pg8::Unit& u, int wr, int wc, int fr, int fq) const {
;     ...
; #pragma unroll
;         for (int ai = 0; ai < 2; ++ai)
; #pragma unroll
;             for (int m = 0; m < 4; ++m)
; #pragma unroll
;                 for (int bj = 0; bj < 2; ++bj)
; #pragma unroll
;                     for (int e = 0; e < 8; ++e)
;                         acc[ai][bj][m][e >> 2][e & 3] *= ub(g1[ai][m][bj][e >> 2], e & 3) * rcpf_(ub(g2[ai][m][bj][e >> 2], e & 3));
	v_cvt_f32_ubyte1_e32 v0, v168
	v_rcp_iflag_f32_e32 v171, v0
	v_cvt_f32_ubyte0_e32 v178, v173
	v_pk_mul_f32 v[172:173], v[174:175], v[178:179]
	v_cvt_f32_ubyte2_e32 v0, v168
	v_pk_mul_f32 v[52:53], v[52:53], v[172:173]
	v_rcp_iflag_f32_e32 v172, v0
	v_cvt_f32_ubyte3_e32 v0, v168
	v_cvt_f32_ubyte1_e32 v177, v166
	v_cvt_f32_ubyte0_e32 v176, v166
	v_rcp_iflag_f32_e32 v173, v0
	v_pk_mul_f32 v[170:171], v[170:171], v[176:177]
	v_cvt_f32_ubyte0_e32 v0, v169
	v_pk_mul_f32 v[48:49], v[48:49], v[170:171]
	v_rcp_iflag_f32_e32 v170, v0
	v_cvt_f32_ubyte1_e32 v0, v169
	v_rcp_iflag_f32_e32 v171, v0
	v_cvt_f32_ubyte3_e32 v175, v166
	v_cvt_f32_ubyte2_e32 v174, v166
	v_cvt_f32_ubyte2_e32 v0, v169
	v_pk_mul_f32 v[172:173], v[172:173], v[174:175]
	v_rcp_iflag_f32_e32 v168, v0
	v_cvt_f32_ubyte3_e32 v0, v169
	v_cvt_f32_ubyte1_e32 v175, v167
	v_cvt_f32_ubyte0_e32 v174, v167
	v_pk_mul_f32 v[50:51], v[50:51], v[172:173]
	v_rcp_iflag_f32_e32 v169, v0
	v_cvt_f32_ubyte3_e32 v173, v167
	v_cvt_f32_ubyte2_e32 v172, v167
	v_pk_mul_f32 v[166:167], v[170:171], v[174:175]
	v_cvt_f32_ubyte0_e32 v0, v164
	v_pk_mul_f32 v[44:45], v[44:45], v[166:167]
	v_rcp_iflag_f32_e32 v166, v0
	v_cvt_f32_ubyte1_e32 v0, v164
	v_rcp_iflag_f32_e32 v167, v0
	v_pk_mul_f32 v[168:169], v[168:169], v[172:173]
	v_cvt_f32_ubyte2_e32 v0, v164
	v_pk_mul_f32 v[46:47], v[46:47], v[168:169]
	v_rcp_iflag_f32_e32 v168, v0
	v_cvt_f32_ubyte3_e32 v0, v164
	v_cvt_f32_ubyte1_e32 v173, v162
	v_cvt_f32_ubyte0_e32 v172, v162
	v_rcp_iflag_f32_e32 v169, v0
	v_pk_mul_f32 v[166:167], v[166:167], v[172:173]
	v_cvt_f32_ubyte0_e32 v0, v165
	v_pk_mul_f32 v[40:41], v[40:41], v[166:167]
	v_rcp_iflag_f32_e32 v166, v0
	v_cvt_f32_ubyte1_e32 v0, v165
	v_rcp_iflag_f32_e32 v167, v0
	v_cvt_f32_ubyte3_e32 v171, v162
	v_cvt_f32_ubyte2_e32 v170, v162
	v_cvt_f32_ubyte2_e32 v0, v165
	v_pk_mul_f32 v[168:169], v[168:169], v[170:171]
	v_rcp_iflag_f32_e32 v164, v0
	v_cvt_f32_ubyte3_e32 v0, v165
	v_cvt_f32_ubyte1_e32 v171, v163
	v_cvt_f32_ubyte0_e32 v170, v163
	v_pk_mul_f32 v[42:43], v[42:43], v[168:169]
	v_rcp_iflag_f32_e32 v165, v0
	v_cvt_f32_ubyte3_e32 v169, v163
	v_cvt_f32_ubyte2_e32 v168, v163
	v_pk_mul_f32 v[162:163], v[166:167], v[170:171]
	v_cvt_f32_ubyte0_e32 v0, v160
	v_pk_mul_f32 v[36:37], v[36:37], v[162:163]
	v_rcp_iflag_f32_e32 v162, v0
	v_cvt_f32_ubyte1_e32 v0, v160
	v_rcp_iflag_f32_e32 v163, v0
	v_pk_mul_f32 v[164:165], v[164:165], v[168:169]
	v_cvt_f32_ubyte2_e32 v0, v160
	v_pk_mul_f32 v[38:39], v[38:39], v[164:165]
	v_rcp_iflag_f32_e32 v164, v0
	v_cvt_f32_ubyte3_e32 v0, v160
	v_cvt_f32_ubyte1_e32 v169, v158
	v_cvt_f32_ubyte0_e32 v168, v158
	v_rcp_iflag_f32_e32 v165, v0
	v_pk_mul_f32 v[162:163], v[162:163], v[168:169]
	v_cvt_f32_ubyte0_e32 v0, v161
	v_pk_mul_f32 v[32:33], v[32:33], v[162:163]
	v_rcp_iflag_f32_e32 v162, v0
	v_cvt_f32_ubyte1_e32 v0, v161
	v_rcp_iflag_f32_e32 v163, v0
	v_cvt_f32_ubyte3_e32 v167, v158
	v_cvt_f32_ubyte2_e32 v166, v158
	v_cvt_f32_ubyte2_e32 v0, v161
	v_pk_mul_f32 v[164:165], v[164:165], v[166:167]
	v_rcp_iflag_f32_e32 v160, v0
	v_cvt_f32_ubyte3_e32 v0, v161
	v_cvt_f32_ubyte1_e32 v167, v159
	v_cvt_f32_ubyte0_e32 v166, v159
	v_pk_mul_f32 v[34:35], v[34:35], v[164:165]
	v_rcp_iflag_f32_e32 v161, v0
	v_cvt_f32_ubyte3_e32 v165, v159
	v_cvt_f32_ubyte2_e32 v164, v159
	v_pk_mul_f32 v[158:159], v[162:163], v[166:167]
	v_cvt_f32_ubyte0_e32 v0, v154
	v_pk_mul_f32 v[28:29], v[28:29], v[158:159]
	v_rcp_iflag_f32_e32 v158, v0
	v_cvt_f32_ubyte1_e32 v0, v154
	v_rcp_iflag_f32_e32 v159, v0
	v_pk_mul_f32 v[160:161], v[160:161], v[164:165]
	v_cvt_f32_ubyte2_e32 v0, v154
	v_pk_mul_f32 v[30:31], v[30:31], v[160:161]
	v_rcp_iflag_f32_e32 v160, v0
	v_cvt_f32_ubyte3_e32 v0, v154
	v_cvt_f32_ubyte1_e32 v165, v156
	v_cvt_f32_ubyte0_e32 v164, v156
	v_rcp_iflag_f32_e32 v161, v0
	v_pk_mul_f32 v[158:159], v[158:159], v[164:165]
	v_cvt_f32_ubyte0_e32 v0, v155
	v_pk_mul_f32 v[24:25], v[24:25], v[158:159]
	v_rcp_iflag_f32_e32 v158, v0
	v_cvt_f32_ubyte1_e32 v0, v155
	v_rcp_iflag_f32_e32 v159, v0
	v_cvt_f32_ubyte2_e32 v0, v155
	v_rcp_iflag_f32_e32 v154, v0
	v_cvt_f32_ubyte3_e32 v0, v155
	v_rcp_iflag_f32_e32 v155, v0
	v_cvt_f32_ubyte3_e32 v163, v156
	v_cvt_f32_ubyte2_e32 v162, v156
	v_pk_mul_f32 v[160:161], v[160:161], v[162:163]
	v_cvt_f32_ubyte0_e32 v0, v152
	v_pk_mul_f32 v[26:27], v[26:27], v[160:161]
	v_cvt_f32_ubyte3_e32 v161, v157
	v_cvt_f32_ubyte2_e32 v160, v157
	v_pk_mul_f32 v[154:155], v[154:155], v[160:161]
	v_cvt_f32_ubyte1_e32 v163, v157
	v_pk_mul_f32 v[22:23], v[22:23], v[154:155]
	v_rcp_iflag_f32_e32 v154, v0
	v_cvt_f32_ubyte1_e32 v0, v152
	v_rcp_iflag_f32_e32 v155, v0
	v_cvt_f32_ubyte0_e32 v162, v157
	v_pk_mul_f32 v[156:157], v[158:159], v[162:163]
	v_cvt_f32_ubyte2_e32 v0, v152
	v_pk_mul_f32 v[20:21], v[20:21], v[156:157]
	v_rcp_iflag_f32_e32 v156, v0
	v_cvt_f32_ubyte3_e32 v0, v152
	v_cvt_f32_ubyte1_e32 v161, v150
	v_cvt_f32_ubyte0_e32 v160, v150
	v_rcp_iflag_f32_e32 v157, v0
	v_pk_mul_f32 v[154:155], v[154:155], v[160:161]
	v_cvt_f32_ubyte0_e32 v0, v153
	v_pk_mul_f32 v[16:17], v[16:17], v[154:155]
	v_rcp_iflag_f32_e32 v154, v0
	v_cvt_f32_ubyte1_e32 v0, v153
	v_rcp_iflag_f32_e32 v155, v0
	v_cvt_f32_ubyte3_e32 v159, v150
	v_cvt_f32_ubyte2_e32 v158, v150
	v_cvt_f32_ubyte2_e32 v0, v153
	v_pk_mul_f32 v[156:157], v[156:157], v[158:159]
	v_rcp_iflag_f32_e32 v152, v0
	v_cvt_f32_ubyte3_e32 v0, v153
	v_cvt_f32_ubyte1_e32 v159, v151
	v_cvt_f32_ubyte0_e32 v158, v151
	v_pk_mul_f32 v[18:19], v[18:19], v[156:157]
	v_rcp_iflag_f32_e32 v153, v0
	v_cvt_f32_ubyte3_e32 v157, v151
	v_cvt_f32_ubyte2_e32 v156, v151
	v_pk_mul_f32 v[150:151], v[154:155], v[158:159]
	v_cvt_f32_ubyte0_e32 v0, v148
	v_pk_mul_f32 v[12:13], v[12:13], v[150:151]
	v_rcp_iflag_f32_e32 v150, v0
	v_cvt_f32_ubyte1_e32 v0, v148
	v_rcp_iflag_f32_e32 v151, v0
	v_pk_mul_f32 v[152:153], v[152:153], v[156:157]
	v_cvt_f32_ubyte2_e32 v0, v148
	v_pk_mul_f32 v[14:15], v[14:15], v[152:153]
	v_rcp_iflag_f32_e32 v152, v0
	v_cvt_f32_ubyte3_e32 v0, v148
	v_cvt_f32_ubyte1_e32 v157, v2
	v_cvt_f32_ubyte0_e32 v156, v2
	v_rcp_iflag_f32_e32 v153, v0
	v_pk_mul_f32 v[150:151], v[150:151], v[156:157]
	v_cvt_f32_ubyte0_e32 v0, v149
	v_pk_mul_f32 v[8:9], v[8:9], v[150:151]
	v_rcp_iflag_f32_e32 v150, v0
	v_cvt_f32_ubyte1_e32 v0, v149
	v_rcp_iflag_f32_e32 v151, v0
	v_cvt_f32_ubyte2_e32 v0, v149
	v_rcp_iflag_f32_e32 v148, v0
	v_cvt_f32_ubyte3_e32 v0, v149
	v_rcp_iflag_f32_e32 v149, v0
	v_cvt_f32_ubyte3_e32 v155, v2
	v_cvt_f32_ubyte2_e32 v154, v2
	v_pk_mul_f32 v[152:153], v[152:153], v[154:155]
	v_cvt_f32_ubyte1_e32 v155, v3
	v_pk_mul_f32 v[10:11], v[10:11], v[152:153]
	v_cvt_f32_ubyte3_e32 v153, v3
	v_cvt_f32_ubyte2_e32 v152, v3
	v_cvt_f32_ubyte0_e32 v154, v3
	v_pk_mul_f32 v[2:3], v[150:151], v[154:155]
	v_pk_mul_f32 v[148:149], v[148:149], v[152:153]
	v_pk_mul_f32 v[4:5], v[4:5], v[2:3]
	v_pk_mul_f32 v[6:7], v[6:7], v[148:149]
	s_branch .LBB0_448
